# speedup vs baseline: 1.0053x; 1.0053x over previous
; __device__ __forceinline__ void row_phase(KP p, int layer, int mode, int tix) {
;   const int lane = tix & 63;
;   const int gw = blockIdx.x * (NTHREADS / 64) + (tix >> 6);
;   const int nw = gridDim.x * (NTHREADS / 64);
;   float* X = (float*)(p->ws + OFF_X);
;   u16* H = (u16*)(p->ws + OFF_H);
;   const float* mixo = (const float*)(p->ws + OFF_R);
;   for (int row = gw; row < MP; row += nw) {
;     const int b = row / LP, pos = row % LP;
;     u16* hrow = H + (size_t)row * DM;
;     float* xrow = X + (size_t)row * DM;
;     if (pos < PADF) {
;     ...
;       const float* g = p->in[mode == 1 ? I_NPOST : I_NFPOST] + (size_t)layer * DM;
; #pragma unroll
;       for (int i = 0; i < 8; ++i) {
;         float4 gg = *(const float4*)(g + lane * 4 + i * 256);
;         v[i].x += d[i].x * rs * gg.x; v[i].y += d[i].y * rs * gg.y; v[i].z += d[i].z * rs * gg.z; v[i].w += d[i].w * rs * gg.w;
;       }
;       if (mode == 2 && layer == 1) {
;         if (pos >= 128) {
;           float* o = p->out + ((size_t)b * 8192 + (pos - 128)) * DM;
; #pragma unroll
;           for (int i = 0; i < 8; ++i) *(float4*)(o + lane * 4 + i * 256) = v[i];
;         }
;         continue;
;       }
; #pragma unroll
;       for (int i = 0; i < 8; ++i) *(float4*)(xrow + lane * 4 + i * 256) = v[i];
;     }
;     {
;       float ss = 0.f;
; #pragma unroll
;       for (int i = 0; i < 8; ++i) ss += v[i].x * v[i].x + v[i].y * v[i].y + v[i].z * v[i].z + v[i].w * v[i].w;
;       ss = wave_sum(ss);
;       const float rs = rsqrtf(ss * (1.0f / DM) + 1e-6f);
;       const float* g = (mode == 1) ? (p->in[I_NFPRE] + (size_t)layer * DM) : (p->in[I_NPRE] + (size_t)(mode == 2 ? 1 : 0) * DM);
; #pragma unroll
;       for (int i = 0; i < 8; ++i) {
;         float4 gg = *(const float4*)(g + lane * 4 + i * 256);
.LBB0_165:
	s_andn2_b64 vcc, exec, s[4:5]
	s_cbranch_vccnz .LBB0_184
	s_mov_b32 s4, 0
	s_nop 0
	v_mbcnt_lo_u32_b32 v0, -1, s4
	v_mbcnt_hi_u32_b32 v0, -1, v0
	v_add_u32_e32 v2, s3, v0
	v_ashrrev_i32_e32 v2, 6, v2
	v_readlane_b32 s4, v245, 0
	s_nop 1
	v_add_u32_e32 v66, s4, v2
	s_movk_i32 s4, 0x4100
	v_cmp_gt_i32_e32 vcc, s4, v66
	s_and_saveexec_b64 s[8:9], vcc
	s_cbranch_execz .LBB0_183
	v_readlane_b32 s4, v245, 1
	v_readlane_b32 s5, v245, 2
	s_load_dword s4, s[4:5], 0x0
	v_lshlrev_b32_e32 v0, 2, v0
	v_and_b32_e32 v68, 0xfc, v0
	s_add_i32 s5, s94, -9
	v_lshlrev_b32_e32 v0, 2, v68
	s_waitcnt lgkmcnt(0)
	s_lshl_b32 s18, s4, 3
	s_cmp_gt_u32 s5, 7
	v_lshl_add_u64 v[2:3], s[80:81], 0, v[0:1]
	s_mov_b64 s[4:5], 0xc300000
	s_cselect_b64 s[10:11], -1, 0
	v_lshl_add_u64 v[70:71], v[2:3], 0, s[4:5]
	s_ashr_i32 s37, s36, 31
	s_mov_b64 s[4:5], 0x1eaa0000
	s_lshl_b64 s[12:13], s[36:37], 13
	v_lshl_add_u64 v[72:73], v[2:3], 0, s[4:5]
	s_mov_b64 s[14:15], 0
	s_load_dwordx4 s[4:7], s[96:97], 0xb8
	v_lshlrev_b32_e32 v0, 2, v68
	s_waitcnt lgkmcnt(0)
	s_add_u32 s4, s4, s12
	s_addc_u32 s5, s5, s13
	s_add_u32 s6, s6, s12
	s_addc_u32 s7, s7, s13
	global_load_dwordx4 v[184:187], v0, s[4:5] offset:1024
	global_load_dwordx4 v[188:191], v0, s[4:5] offset:2048
	global_load_dwordx4 v[192:195], v0, s[4:5] offset:3072
	s_add_u32 s4, s4, 0x1000
	s_addc_u32 s5, s5, 0
	global_load_dwordx4 v[196:199], v0, s[4:5]
	global_load_dwordx4 v[200:203], v0, s[4:5] offset:1024
	global_load_dwordx4 v[204:207], v0, s[4:5] offset:2048
	global_load_dwordx4 v[208:211], v0, s[4:5] offset:3072
	global_load_dwordx4 v[212:215], v0, s[6:7]
	global_load_dwordx4 v[216:219], v0, s[6:7] offset:1024
	global_load_dwordx4 v[220:223], v0, s[6:7] offset:2048
	global_load_dwordx4 v[224:227], v0, s[6:7] offset:3072
	s_add_u32 s6, s6, 0x1000
	s_addc_u32 s7, s7, 0
	global_load_dwordx4 v[228:231], v0, s[6:7]
	global_load_dwordx4 v[232:235], v0, s[6:7] offset:1024
	global_load_dwordx4 v[236:239], v0, s[6:7] offset:2048
	global_load_dwordx4 v[240:243], v0, s[6:7] offset:3072
	s_waitcnt vmcnt(0)
	s_branch .LBB0_169

; __device__ __forceinline__ void row_phase(KP p, int layer, int mode, int tix) {
;     ...
;       if (row >= MSPLIT) {
;         const float* sl = (const float*)(p->ws + OFF_SLAB) + (size_t)(row - MSPLIT) * DM;
;         const int ns = (mode == 1) ? 8 : 4;
; #pragma unroll
;         for (int i = 0; i < 8; ++i) d[i] = *(const float4*)(sl + lane * 4 + i * 256);
;         for (int s = 1; s < ns; ++s) {
;           const float* sp = sl + (size_t)s * 256 * DM;
; #pragma unroll
;           for (int i = 0; i < 8; ++i) { float4 t = *(const float4*)(sp + lane * 4 + i * 256); d[i].x += t.x; d[i].y += t.y; d[i].z += t.z; d[i].w += t.w; }
;         }
.LBB0_178:
	s_andn2_saveexec_b64 s[4:5], s[4:5]
	s_cbranch_execz .LBB0_180
	s_waitcnt vmcnt(0)
	v_add_u32_e32 v34, 0xffffc000, v66
	v_mov_b32_e32 v35, v1
	v_lshlrev_b64 v[34:35], 13, v[34:35]
	v_lshl_add_u64 v[34:35], v[72:73], 0, v[34:35]
	s_mov_b32 s6, 0x1000
	s_mov_b32 s7, 0
	v_lshl_add_u64 v[86:87], v[34:35], 0, s[6:7]
	s_mov_b32 s6, 0x200000
	global_load_dwordx4 v[42:45], v[34:35], off
	global_load_dwordx4 v[38:41], v[34:35], off offset:1024
	global_load_dwordx4 v[78:81], v[34:35], off offset:2048
	global_load_dwordx4 v[46:49], v[34:35], off offset:3072
	global_load_dwordx4 v[58:61], v[86:87], off
	global_load_dwordx4 v[54:57], v[86:87], off offset:1024
	global_load_dwordx4 v[50:53], v[86:87], off offset:2048
	global_load_dwordx4 v[62:65], v[86:87], off offset:3072
	v_lshl_add_u64 v[34:35], v[34:35], 0, s[6:7]
	v_lshl_add_u64 v[86:87], v[86:87], 0, s[6:7]
	global_load_dwordx4 v[88:91], v[34:35], off
	global_load_dwordx4 v[92:95], v[34:35], off offset:1024
	global_load_dwordx4 v[96:99], v[34:35], off offset:2048
	global_load_dwordx4 v[100:103], v[34:35], off offset:3072
	global_load_dwordx4 v[104:107], v[86:87], off
	global_load_dwordx4 v[108:111], v[86:87], off offset:1024
	global_load_dwordx4 v[112:115], v[86:87], off offset:2048
	global_load_dwordx4 v[116:119], v[86:87], off offset:3072
	s_waitcnt vmcnt(0)
	v_pk_add_f32 v[42:43], v[42:43], v[88:89]
	v_pk_add_f32 v[44:45], v[44:45], v[90:91]
	v_pk_add_f32 v[38:39], v[38:39], v[92:93]
	v_pk_add_f32 v[40:41], v[40:41], v[94:95]
	v_pk_add_f32 v[78:79], v[78:79], v[96:97]
	v_pk_add_f32 v[80:81], v[80:81], v[98:99]
	v_pk_add_f32 v[46:47], v[46:47], v[100:101]
	v_pk_add_f32 v[48:49], v[48:49], v[102:103]
	v_pk_add_f32 v[58:59], v[58:59], v[104:105]
	v_pk_add_f32 v[60:61], v[60:61], v[106:107]
	v_pk_add_f32 v[54:55], v[54:55], v[108:109]
	v_pk_add_f32 v[56:57], v[56:57], v[110:111]
	v_pk_add_f32 v[50:51], v[50:51], v[112:113]
	v_pk_add_f32 v[52:53], v[52:53], v[114:115]
	v_pk_add_f32 v[62:63], v[62:63], v[116:117]
	v_pk_add_f32 v[64:65], v[64:65], v[118:119]
	v_lshl_add_u64 v[34:35], v[34:35], 0, s[6:7]
	v_lshl_add_u64 v[86:87], v[86:87], 0, s[6:7]
	global_load_dwordx4 v[88:91], v[34:35], off
	global_load_dwordx4 v[92:95], v[34:35], off offset:1024
	global_load_dwordx4 v[96:99], v[34:35], off offset:2048
	global_load_dwordx4 v[100:103], v[34:35], off offset:3072
	global_load_dwordx4 v[104:107], v[86:87], off
	global_load_dwordx4 v[108:111], v[86:87], off offset:1024
	global_load_dwordx4 v[112:115], v[86:87], off offset:2048
	global_load_dwordx4 v[116:119], v[86:87], off offset:3072
	s_waitcnt vmcnt(0)
	v_pk_add_f32 v[42:43], v[42:43], v[88:89]
	v_pk_add_f32 v[44:45], v[44:45], v[90:91]
	v_pk_add_f32 v[38:39], v[38:39], v[92:93]
	v_pk_add_f32 v[40:41], v[40:41], v[94:95]
	v_pk_add_f32 v[78:79], v[78:79], v[96:97]
	v_pk_add_f32 v[80:81], v[80:81], v[98:99]
	v_pk_add_f32 v[46:47], v[46:47], v[100:101]
	v_pk_add_f32 v[48:49], v[48:49], v[102:103]
	v_pk_add_f32 v[58:59], v[58:59], v[104:105]
	v_pk_add_f32 v[60:61], v[60:61], v[106:107]
	v_pk_add_f32 v[54:55], v[54:55], v[108:109]
	v_pk_add_f32 v[56:57], v[56:57], v[110:111]
	v_pk_add_f32 v[50:51], v[50:51], v[112:113]
	v_pk_add_f32 v[52:53], v[52:53], v[114:115]
	v_pk_add_f32 v[62:63], v[62:63], v[116:117]
	v_pk_add_f32 v[64:65], v[64:65], v[118:119]
	v_lshl_add_u64 v[34:35], v[34:35], 0, s[6:7]
	v_lshl_add_u64 v[86:87], v[86:87], 0, s[6:7]
	global_load_dwordx4 v[88:91], v[34:35], off
	global_load_dwordx4 v[92:95], v[34:35], off offset:1024
	global_load_dwordx4 v[96:99], v[34:35], off offset:2048
	global_load_dwordx4 v[100:103], v[34:35], off offset:3072
	global_load_dwordx4 v[104:107], v[86:87], off
	global_load_dwordx4 v[108:111], v[86:87], off offset:1024
	global_load_dwordx4 v[112:115], v[86:87], off offset:2048
	global_load_dwordx4 v[116:119], v[86:87], off offset:3072
	s_waitcnt vmcnt(0)
	v_pk_add_f32 v[42:43], v[42:43], v[88:89]
	v_pk_add_f32 v[44:45], v[44:45], v[90:91]
	v_pk_add_f32 v[38:39], v[38:39], v[92:93]
	v_pk_add_f32 v[40:41], v[40:41], v[94:95]
	v_pk_add_f32 v[78:79], v[78:79], v[96:97]
	v_pk_add_f32 v[80:81], v[80:81], v[98:99]
	v_pk_add_f32 v[46:47], v[46:47], v[100:101]
	v_pk_add_f32 v[48:49], v[48:49], v[102:103]
	v_pk_add_f32 v[58:59], v[58:59], v[104:105]
	v_pk_add_f32 v[60:61], v[60:61], v[106:107]
	v_pk_add_f32 v[54:55], v[54:55], v[108:109]
	v_pk_add_f32 v[56:57], v[56:57], v[110:111]
	v_pk_add_f32 v[50:51], v[50:51], v[112:113]
	v_pk_add_f32 v[52:53], v[52:53], v[114:115]
	v_pk_add_f32 v[62:63], v[62:63], v[116:117]
	v_pk_add_f32 v[64:65], v[64:65], v[118:119]
	v_lshl_add_u64 v[34:35], v[34:35], 0, s[6:7]
	v_lshl_add_u64 v[86:87], v[86:87], 0, s[6:7]
	global_load_dwordx4 v[88:91], v[34:35], off
	global_load_dwordx4 v[92:95], v[34:35], off offset:1024
	global_load_dwordx4 v[96:99], v[34:35], off offset:2048
	global_load_dwordx4 v[100:103], v[34:35], off offset:3072
	global_load_dwordx4 v[104:107], v[86:87], off
	global_load_dwordx4 v[108:111], v[86:87], off offset:1024
	global_load_dwordx4 v[112:115], v[86:87], off offset:2048
	global_load_dwordx4 v[116:119], v[86:87], off offset:3072
	s_waitcnt vmcnt(0)
; __device__ __forceinline__ void row_phase(KP p, int layer, int mode, int tix) {
;     ...
;       if (row >= MSPLIT) {
;         const float* sl = (const float*)(p->ws + OFF_SLAB) + (size_t)(row - MSPLIT) * DM;
;         const int ns = (mode == 1) ? 8 : 4;
; #pragma unroll
;         for (int i = 0; i < 8; ++i) d[i] = *(const float4*)(sl + lane * 4 + i * 256);
;         for (int s = 1; s < ns; ++s) {
;           const float* sp = sl + (size_t)s * 256 * DM;
; #pragma unroll
;           for (int i = 0; i < 8; ++i) { float4 t = *(const float4*)(sp + lane * 4 + i * 256); d[i].x += t.x; d[i].y += t.y; d[i].z += t.z; d[i].w += t.w; }
;         }
	v_pk_add_f32 v[42:43], v[42:43], v[88:89]
	v_pk_add_f32 v[44:45], v[44:45], v[90:91]
	v_pk_add_f32 v[38:39], v[38:39], v[92:93]
	v_pk_add_f32 v[40:41], v[40:41], v[94:95]
	v_pk_add_f32 v[78:79], v[78:79], v[96:97]
	v_pk_add_f32 v[80:81], v[80:81], v[98:99]
	v_pk_add_f32 v[46:47], v[46:47], v[100:101]
	v_pk_add_f32 v[48:49], v[48:49], v[102:103]
	v_pk_add_f32 v[58:59], v[58:59], v[104:105]
	v_pk_add_f32 v[60:61], v[60:61], v[106:107]
	v_pk_add_f32 v[54:55], v[54:55], v[108:109]
	v_pk_add_f32 v[56:57], v[56:57], v[110:111]
	v_pk_add_f32 v[50:51], v[50:51], v[112:113]
	v_pk_add_f32 v[52:53], v[52:53], v[114:115]
	v_pk_add_f32 v[62:63], v[62:63], v[116:117]
	v_pk_add_f32 v[64:65], v[64:65], v[118:119]
	v_lshl_add_u64 v[34:35], v[34:35], 0, s[6:7]
	v_lshl_add_u64 v[86:87], v[86:87], 0, s[6:7]
	global_load_dwordx4 v[88:91], v[34:35], off
	global_load_dwordx4 v[92:95], v[34:35], off offset:1024
	global_load_dwordx4 v[96:99], v[34:35], off offset:2048
	global_load_dwordx4 v[100:103], v[34:35], off offset:3072
	global_load_dwordx4 v[104:107], v[86:87], off
	global_load_dwordx4 v[108:111], v[86:87], off offset:1024
	global_load_dwordx4 v[112:115], v[86:87], off offset:2048
	global_load_dwordx4 v[116:119], v[86:87], off offset:3072
	s_waitcnt vmcnt(0)
	v_pk_add_f32 v[42:43], v[42:43], v[88:89]
	v_pk_add_f32 v[44:45], v[44:45], v[90:91]
	v_pk_add_f32 v[38:39], v[38:39], v[92:93]
	v_pk_add_f32 v[40:41], v[40:41], v[94:95]
	v_pk_add_f32 v[78:79], v[78:79], v[96:97]
	v_pk_add_f32 v[80:81], v[80:81], v[98:99]
	v_pk_add_f32 v[46:47], v[46:47], v[100:101]
	v_pk_add_f32 v[48:49], v[48:49], v[102:103]
	v_pk_add_f32 v[58:59], v[58:59], v[104:105]
	v_pk_add_f32 v[60:61], v[60:61], v[106:107]
	v_pk_add_f32 v[54:55], v[54:55], v[108:109]
	v_pk_add_f32 v[56:57], v[56:57], v[110:111]
	v_pk_add_f32 v[50:51], v[50:51], v[112:113]
	v_pk_add_f32 v[52:53], v[52:53], v[114:115]
	v_pk_add_f32 v[62:63], v[62:63], v[116:117]
	v_pk_add_f32 v[64:65], v[64:65], v[118:119]
	v_lshl_add_u64 v[34:35], v[34:35], 0, s[6:7]
	v_lshl_add_u64 v[86:87], v[86:87], 0, s[6:7]
	global_load_dwordx4 v[88:91], v[34:35], off
	global_load_dwordx4 v[92:95], v[34:35], off offset:1024
	global_load_dwordx4 v[96:99], v[34:35], off offset:2048
	global_load_dwordx4 v[100:103], v[34:35], off offset:3072
	global_load_dwordx4 v[104:107], v[86:87], off
	global_load_dwordx4 v[108:111], v[86:87], off offset:1024
	global_load_dwordx4 v[112:115], v[86:87], off offset:2048
	global_load_dwordx4 v[116:119], v[86:87], off offset:3072
	s_waitcnt vmcnt(0)
	v_pk_add_f32 v[42:43], v[42:43], v[88:89]
	v_pk_add_f32 v[44:45], v[44:45], v[90:91]
	v_pk_add_f32 v[38:39], v[38:39], v[92:93]
	v_pk_add_f32 v[40:41], v[40:41], v[94:95]
	v_pk_add_f32 v[78:79], v[78:79], v[96:97]
	v_pk_add_f32 v[80:81], v[80:81], v[98:99]
	v_pk_add_f32 v[46:47], v[46:47], v[100:101]
	v_pk_add_f32 v[48:49], v[48:49], v[102:103]
	v_pk_add_f32 v[58:59], v[58:59], v[104:105]
	v_pk_add_f32 v[60:61], v[60:61], v[106:107]
	v_pk_add_f32 v[54:55], v[54:55], v[108:109]
	v_pk_add_f32 v[56:57], v[56:57], v[110:111]
	v_pk_add_f32 v[50:51], v[50:51], v[112:113]
	v_pk_add_f32 v[52:53], v[52:53], v[114:115]
	v_pk_add_f32 v[62:63], v[62:63], v[116:117]
	v_pk_add_f32 v[64:65], v[64:65], v[118:119]
	v_lshl_add_u64 v[34:35], v[34:35], 0, s[6:7]
	v_lshl_add_u64 v[86:87], v[86:87], 0, s[6:7]
	global_load_dwordx4 v[88:91], v[34:35], off
	global_load_dwordx4 v[92:95], v[34:35], off offset:1024
	global_load_dwordx4 v[96:99], v[34:35], off offset:2048
	global_load_dwordx4 v[100:103], v[34:35], off offset:3072
	global_load_dwordx4 v[104:107], v[86:87], off
	global_load_dwordx4 v[108:111], v[86:87], off offset:1024
	global_load_dwordx4 v[112:115], v[86:87], off offset:2048
	global_load_dwordx4 v[116:119], v[86:87], off offset:3072
	s_waitcnt vmcnt(0)
	v_pk_add_f32 v[42:43], v[42:43], v[88:89]
	v_pk_add_f32 v[44:45], v[44:45], v[90:91]
	v_pk_add_f32 v[38:39], v[38:39], v[92:93]
	v_pk_add_f32 v[40:41], v[40:41], v[94:95]
	v_pk_add_f32 v[78:79], v[78:79], v[96:97]
	v_pk_add_f32 v[80:81], v[80:81], v[98:99]
	v_pk_add_f32 v[46:47], v[46:47], v[100:101]
	v_pk_add_f32 v[48:49], v[48:49], v[102:103]
	v_pk_add_f32 v[58:59], v[58:59], v[104:105]
	v_pk_add_f32 v[60:61], v[60:61], v[106:107]
	v_pk_add_f32 v[54:55], v[54:55], v[108:109]
	v_pk_add_f32 v[56:57], v[56:57], v[110:111]
	v_pk_add_f32 v[50:51], v[50:51], v[112:113]
	v_pk_add_f32 v[52:53], v[52:53], v[114:115]
	v_pk_add_f32 v[62:63], v[62:63], v[116:117]
	v_pk_add_f32 v[64:65], v[64:65], v[118:119]
	v_mov_b64_e32 v[34:35], v[78:79]
	v_mov_b64_e32 v[36:37], v[80:81]
; __device__ __forceinline__ void row_phase(KP p, int layer, int mode, int tix) {
;     ...
;       float ss = 0.f;
; #pragma unroll
;       for (int i = 0; i < 8; ++i) ss += d[i].x * d[i].x + d[i].y * d[i].y + d[i].z * d[i].z + d[i].w * d[i].w;
;       ss = wave_sum(ss);
;       const float rs = rsqrtf(ss * (1.0f / DM) + 1e-6f);
;       const float* g = p->in[mode == 1 ? I_NPOST : I_NFPOST] + (size_t)layer * DM;
; #pragma unroll
;       for (int i = 0; i < 8; ++i) {
;         float4 gg = *(const float4*)(g + lane * 4 + i * 256);
;         v[i].x += d[i].x * rs * gg.x; v[i].y += d[i].y * rs * gg.y; v[i].z += d[i].z * rs * gg.z; v[i].w += d[i].w * rs * gg.w;
;       }
;     ...
;       for (int i = 0; i < 8; ++i) *(float4*)(xrow + lane * 4 + i * 256) = v[i];
;     }
;     {
;       float ss = 0.f;
; #pragma unroll
;       for (int i = 0; i < 8; ++i) ss += v[i].x * v[i].x + v[i].y * v[i].y + v[i].z * v[i].z + v[i].w * v[i].w;
.LBB0_180:
	s_or_b64 exec, exec, s[4:5]
	s_load_dwordx4 s[4:7], s[96:97], 0xb8
	s_waitcnt vmcnt(7)
	v_pk_mul_f32 v[78:79], v[42:43], v[42:43]
	v_pk_mul_f32 v[80:81], v[44:45], v[44:45]
	v_add_f32_e32 v67, v79, v78
	s_waitcnt vmcnt(6)
	v_pk_mul_f32 v[82:83], v[38:39], v[38:39]
	s_waitcnt lgkmcnt(0)
	s_add_u32 s4, s4, s12
	v_add_f32_e32 v67, v80, v67
	s_addc_u32 s5, s5, s13
	v_add_f32_e32 v67, v81, v67
	v_add_f32_e32 v69, v83, v82
	global_load_dwordx4 v[80:83], v0, s[4:5]
	v_pk_mul_f32 v[84:85], v[40:41], v[40:41]
	s_waitcnt vmcnt(6)
	v_pk_mul_f32 v[86:87], v[34:35], v[34:35]
	v_add_f32_e32 v69, v84, v69
	v_add_f32_e32 v69, v85, v69
	v_pk_mul_f32 v[88:89], v[36:37], v[36:37]
	v_add_f32_e32 v67, v69, v67
	v_add_f32_e32 v69, v87, v86
	v_add_f32_e32 v69, v88, v69
	s_waitcnt vmcnt(5)
	v_pk_mul_f32 v[90:91], v[46:47], v[46:47]
	v_add_f32_e32 v69, v89, v69
	v_pk_mul_f32 v[92:93], v[48:49], v[48:49]
	v_add_f32_e32 v67, v69, v67
	v_add_f32_e32 v69, v91, v90
	v_add_f32_e32 v69, v92, v69
	s_waitcnt vmcnt(4)
	v_pk_mul_f32 v[94:95], v[58:59], v[58:59]
	v_add_f32_e32 v69, v93, v69
	v_pk_mul_f32 v[96:97], v[60:61], v[60:61]
	v_add_f32_e32 v67, v69, v67
	v_add_f32_e32 v69, v95, v94
	v_add_f32_e32 v69, v96, v69
	s_waitcnt vmcnt(3)
	v_pk_mul_f32 v[98:99], v[54:55], v[54:55]
	v_add_f32_e32 v69, v97, v69
	v_pk_mul_f32 v[100:101], v[56:57], v[56:57]
	v_add_f32_e32 v67, v69, v67
	v_add_f32_e32 v69, v99, v98
	v_add_f32_e32 v69, v100, v69
	s_waitcnt vmcnt(2)
	v_pk_mul_f32 v[102:103], v[50:51], v[50:51]
	v_add_f32_e32 v69, v101, v69
	v_pk_mul_f32 v[104:105], v[52:53], v[52:53]
	v_add_f32_e32 v67, v69, v67
	v_add_f32_e32 v69, v103, v102
	v_add_f32_e32 v69, v104, v69
	s_waitcnt vmcnt(1)
	v_pk_mul_f32 v[106:107], v[62:63], v[62:63]
	v_add_f32_e32 v69, v105, v69
	v_pk_mul_f32 v[108:109], v[64:65], v[64:65]
	v_add_f32_e32 v67, v69, v67
	v_add_f32_e32 v69, v107, v106
	v_add_f32_e32 v69, v108, v69
	v_add_f32_e32 v69, v109, v69
	v_add_f32_e32 v67, v69, v67
	ds_swizzle_b32 v69, v67 offset:swizzle(SWAP,1)
	v_lshl_add_u64 v[84:85], s[4:5], 0, v[0:1]
	v_lshl_add_u64 v[76:77], v[76:77], 0, v[0:1]
	s_waitcnt lgkmcnt(0)
	v_add_f32_e32 v67, v67, v69
	ds_swizzle_b32 v69, v67 offset:swizzle(SWAP,2)
	s_waitcnt lgkmcnt(0)
	v_add_f32_e32 v67, v67, v69
	ds_swizzle_b32 v69, v67 offset:swizzle(SWAP,4)
	s_waitcnt lgkmcnt(0)
	v_add_f32_e32 v67, v67, v69
	ds_swizzle_b32 v69, v67 offset:swizzle(SWAP,8)
	s_waitcnt lgkmcnt(0)
	v_add_f32_e32 v67, v67, v69
	ds_swizzle_b32 v69, v67 offset:swizzle(SWAP,16)
	s_waitcnt lgkmcnt(0)
	v_add_f32_e32 v67, v67, v69
	v_mov_b32_e32 v69, v67
	s_nop 1
	v_permlane32_swap_b32_e32 v67, v69
	v_add_f32_e32 v67, v67, v69
	v_fmamk_f32 v67, v67, 0x3a000000, v170
	v_cmp_gt_f32_e32 vcc, s91, v67
	v_mul_f32_e32 v69, 0x4b800000, v67
	s_nop 0
	v_cndmask_b32_e32 v67, v67, v69, vcc
	v_rsq_f32_e32 v67, v67
	s_nop 0
	v_mul_f32_e32 v69, 0x45800000, v67
	v_cndmask_b32_e32 v78, v67, v69, vcc
	v_pk_mul_f32 v[42:43], v[42:43], v[78:79] op_sel_hi:[1,0]
	v_pk_mul_f32 v[38:39], v[38:39], v[78:79] op_sel_hi:[1,0]
	s_waitcnt vmcnt(0)
	v_pk_fma_f32 v[30:31], v[80:81], v[42:43], v[30:31]
	v_pk_mul_f32 v[42:43], v[44:45], v[78:79] op_sel_hi:[1,0]
	v_pk_mul_f32 v[34:35], v[34:35], v[78:79] op_sel_hi:[1,0]
	v_pk_fma_f32 v[32:33], v[82:83], v[42:43], v[32:33]
	v_mov_b64_e32 v[42:43], v[184:185]
	v_mov_b64_e32 v[44:45], v[186:187]
	v_pk_fma_f32 v[26:27], v[42:43], v[38:39], v[26:27]
	v_pk_mul_f32 v[38:39], v[40:41], v[78:79] op_sel_hi:[1,0]
	s_nop 0
	v_pk_fma_f32 v[28:29], v[44:45], v[38:39], v[28:29]
	v_mov_b64_e32 v[38:39], v[188:189]
	v_mov_b64_e32 v[40:41], v[190:191]
	v_pk_fma_f32 v[22:23], v[38:39], v[34:35], v[22:23]
	v_pk_mul_f32 v[34:35], v[36:37], v[78:79] op_sel_hi:[1,0]
	v_pk_mul_f32 v[38:39], v[46:47], v[78:79] op_sel_hi:[1,0]
	v_pk_fma_f32 v[24:25], v[34:35], v[40:41], v[24:25]
	v_mov_b64_e32 v[34:35], v[192:193]
	v_mov_b64_e32 v[36:37], v[194:195]
	v_pk_mul_f32 v[40:41], v[58:59], v[78:79] op_sel_hi:[1,0]
	s_add_u32 s4, s6, s12
	v_pk_mul_f32 v[42:43], v[22:23], v[22:23]
	s_addc_u32 s5, s7, s13
	v_pk_mul_f32 v[44:45], v[24:25], v[24:25]
	v_pk_fma_f32 v[18:19], v[38:39], v[34:35], v[18:19]
	v_add_co_u32_e32 v38, vcc, s90, v84
	v_pk_mul_f32 v[34:35], v[48:49], v[78:79] op_sel_hi:[1,0]
	s_nop 0
	v_addc_co_u32_e32 v39, vcc, 0, v85, vcc
	v_pk_fma_f32 v[20:21], v[34:35], v[36:37], v[20:21]
	v_mov_b64_e32 v[34:35], v[196:197]
	v_mov_b64_e32 v[36:37], v[198:199]
	v_pk_mul_f32 v[46:47], v[18:19], v[18:19]
	v_pk_mul_f32 v[48:49], v[20:21], v[20:21]
	v_pk_fma_f32 v[14:15], v[40:41], v[34:35], v[14:15]
	v_pk_mul_f32 v[34:35], v[60:61], v[78:79] op_sel_hi:[1,0]
	v_pk_mul_f32 v[40:41], v[54:55], v[78:79] op_sel_hi:[1,0]
	v_pk_fma_f32 v[16:17], v[34:35], v[36:37], v[16:17]
	v_mov_b64_e32 v[34:35], v[200:201]
	v_mov_b64_e32 v[36:37], v[202:203]
	v_pk_fma_f32 v[10:11], v[40:41], v[34:35], v[10:11]
	v_pk_mul_f32 v[34:35], v[56:57], v[78:79] op_sel_hi:[1,0]
	v_pk_mul_f32 v[40:41], v[50:51], v[78:79] op_sel_hi:[1,0]
	v_pk_fma_f32 v[12:13], v[34:35], v[36:37], v[12:13]
	v_mov_b64_e32 v[34:35], v[204:205]
	v_mov_b64_e32 v[36:37], v[206:207]
	v_pk_mul_f32 v[50:51], v[14:15], v[14:15]
	v_pk_mul_f32 v[54:55], v[10:11], v[10:11]
	v_pk_mul_f32 v[56:57], v[12:13], v[12:13]
	v_pk_fma_f32 v[6:7], v[40:41], v[34:35], v[6:7]
	v_pk_mul_f32 v[34:35], v[52:53], v[78:79] op_sel_hi:[1,0]
	v_pk_mul_f32 v[40:41], v[28:29], v[28:29]
	v_pk_fma_f32 v[8:9], v[34:35], v[36:37], v[8:9]
	v_mov_b64_e32 v[34:35], v[208:209]
	v_mov_b64_e32 v[36:37], v[210:211]
	v_pk_mul_f32 v[38:39], v[62:63], v[78:79] op_sel_hi:[1,0]
	global_store_dwordx4 v[76:77], v[30:33], off
	global_store_dwordx4 v[76:77], v[26:29], off offset:1024
; DEVI unsigned pack2(float a, float b) { unsigned r; asm("v_cvt_pk_bf16_f32 %0, %1, %2" : "=v"(r) : "v"(a), "v"(b)); return r; }
; __device__ __forceinline__ void row_phase(KP p, int layer, int mode, int tix) {
;     ...
;       for (int i = 0; i < 8; ++i) *(float4*)(xrow + lane * 4 + i * 256) = v[i];
;     }
;     {
;       float ss = 0.f;
; #pragma unroll
;       for (int i = 0; i < 8; ++i) ss += v[i].x * v[i].x + v[i].y * v[i].y + v[i].z * v[i].z + v[i].w * v[i].w;
;       ss = wave_sum(ss);
;       const float rs = rsqrtf(ss * (1.0f / DM) + 1e-6f);
;       const float* g = (mode == 1) ? (p->in[I_NFPRE] + (size_t)layer * DM) : (p->in[I_NPRE] + (size_t)(mode == 2 ? 1 : 0) * DM);
; #pragma unroll
;       for (int i = 0; i < 8; ++i) {
;         float4 gg = *(const float4*)(g + lane * 4 + i * 256);
;         uint2 u;
;         u.x = pack2(v[i].x * rs * gg.x, v[i].y * rs * gg.y);
;         u.y = pack2(v[i].z * rs * gg.z, v[i].w * rs * gg.w);
;         *(uint2*)(hrow + lane * 4 + i * 256) = u;
;       }
	global_store_dwordx4 v[76:77], v[22:25], off offset:2048
	global_store_dwordx4 v[76:77], v[18:21], off offset:3072
	v_pk_mul_f32 v[52:53], v[16:17], v[16:17]
	v_pk_mul_f32 v[58:59], v[6:7], v[6:7]
	v_pk_mul_f32 v[60:61], v[8:9], v[8:9]
	v_pk_fma_f32 v[2:3], v[38:39], v[34:35], v[2:3]
	v_pk_mul_f32 v[34:35], v[64:65], v[78:79] op_sel_hi:[1,0]
	v_pk_mul_f32 v[38:39], v[26:27], v[26:27]
	v_pk_fma_f32 v[4:5], v[34:35], v[36:37], v[4:5]
	v_add_co_u32_e32 v34, vcc, s90, v76
	v_add_f32_e32 v38, v38, v39
	s_nop 0
	v_addc_co_u32_e32 v35, vcc, 0, v77, vcc
	global_store_dwordx4 v[34:35], v[14:17], off
	global_store_dwordx4 v[34:35], v[10:13], off offset:1024
	global_store_dwordx4 v[34:35], v[6:9], off offset:2048
	global_store_dwordx4 v[34:35], v[2:5], off offset:3072
	v_pk_mul_f32 v[34:35], v[30:31], v[30:31]
	v_add_f32_e32 v38, v40, v38
	v_add_f32_e32 v38, v41, v38
	v_add_f32_e32 v34, v34, v35
	v_add_f32_e32 v35, v42, v43
	v_mov_b64_e32 v[40:41], v[212:213]
	v_mov_b64_e32 v[42:43], v[214:215]
	v_pk_mul_f32 v[36:37], v[32:33], v[32:33]
	v_add_f32_e32 v35, v35, v44
	v_add_f32_e32 v34, v36, v34
	v_add_f32_e32 v34, v37, v34
	v_add_f32_e32 v34, v34, v38
	v_add_f32_e32 v35, v35, v45
	v_add_f32_e32 v34, v35, v34
	v_add_f32_e32 v35, v46, v47
	v_add_f32_e32 v35, v35, v48
	v_add_f32_e32 v35, v35, v49
	v_add_f32_e32 v34, v34, v35
	v_add_f32_e32 v35, v50, v51
	v_add_f32_e32 v35, v35, v52
	v_add_f32_e32 v35, v35, v53
	v_add_f32_e32 v34, v34, v35
	v_add_f32_e32 v35, v54, v55
	v_add_f32_e32 v35, v35, v56
	v_add_f32_e32 v35, v35, v57
	v_add_f32_e32 v34, v34, v35
	v_add_f32_e32 v35, v58, v59
	v_add_f32_e32 v35, v35, v60
	v_pk_mul_f32 v[62:63], v[2:3], v[2:3]
	v_add_f32_e32 v35, v35, v61
	v_pk_mul_f32 v[64:65], v[4:5], v[4:5]
	v_add_f32_e32 v34, v34, v35
	v_add_f32_e32 v35, v62, v63
	v_add_f32_e32 v35, v35, v64
	v_add_f32_e32 v35, v35, v65
	v_add_f32_e32 v34, v34, v35
	ds_swizzle_b32 v35, v34 offset:swizzle(SWAP,1)
	v_lshl_add_u64 v[36:37], s[4:5], 0, v[0:1]
	s_waitcnt lgkmcnt(0)
	v_add_f32_e32 v34, v34, v35
	ds_swizzle_b32 v35, v34 offset:swizzle(SWAP,2)
	s_waitcnt lgkmcnt(0)
	v_add_f32_e32 v34, v34, v35
	ds_swizzle_b32 v35, v34 offset:swizzle(SWAP,4)
	s_waitcnt lgkmcnt(0)
	v_add_f32_e32 v34, v34, v35
	ds_swizzle_b32 v35, v34 offset:swizzle(SWAP,8)
	s_waitcnt lgkmcnt(0)
	v_add_f32_e32 v34, v34, v35
	ds_swizzle_b32 v35, v34 offset:swizzle(SWAP,16)
	s_waitcnt lgkmcnt(0)
	v_add_f32_e32 v34, v34, v35
	v_mov_b32_e32 v35, v34
	s_nop 1
	v_permlane32_swap_b32_e32 v34, v35
	v_add_f32_e32 v34, v34, v35
	v_fmamk_f32 v34, v34, 0x3a000000, v170
	v_cmp_gt_f32_e32 vcc, s91, v34
	v_mul_f32_e32 v35, 0x4b800000, v34
	s_nop 0
	v_cndmask_b32_e32 v34, v34, v35, vcc
	v_rsq_f32_e32 v34, v34
	s_nop 0
	v_mul_f32_e32 v35, 0x45800000, v34
	v_cndmask_b32_e32 v38, v34, v35, vcc
	v_mul_f32_e32 v30, v30, v38
	v_mul_f32_e32 v31, v31, v38
	v_lshlrev_b32_e32 v34, 1, v68
	v_mov_b32_e32 v35, v1
	v_lshl_add_u64 v[34:35], v[74:75], 0, v[34:35]
	v_mul_f32_e32 v30, v40, v30
	v_mul_f32_e32 v31, v41, v31
	v_cvt_pk_bf16_f32 v30, v30, v31
	v_mul_f32_e32 v31, v32, v38
	v_mul_f32_e32 v31, v42, v31
	v_mul_f32_e32 v32, v33, v38
	v_mul_f32_e32 v32, v43, v32
	v_cvt_pk_bf16_f32 v31, v31, v32
	global_store_dwordx2 v[34:35], v[30:31], off
	v_mov_b64_e32 v[30:31], v[216:217]
	v_mov_b64_e32 v[32:33], v[218:219]
	v_mul_f32_e32 v26, v26, v38
	v_mul_f32_e32 v27, v27, v38
	v_mul_f32_e32 v22, v22, v38
	v_mul_f32_e32 v23, v23, v38
	v_mul_f32_e32 v26, v30, v26
	v_mul_f32_e32 v27, v31, v27
	v_cvt_pk_bf16_f32 v26, v26, v27
	v_mul_f32_e32 v27, v28, v38
	v_mul_f32_e32 v27, v27, v32
	v_mul_f32_e32 v28, v29, v38
	v_mul_f32_e32 v28, v28, v33
	v_cvt_pk_bf16_f32 v27, v27, v28
	global_store_dwordx2 v[34:35], v[26:27], off offset:512
	v_mov_b64_e32 v[26:27], v[220:221]
	v_mov_b64_e32 v[28:29], v[222:223]
	v_mul_f32_e32 v22, v22, v26
	v_mul_f32_e32 v23, v23, v27
	v_cvt_pk_bf16_f32 v22, v22, v23
	v_mul_f32_e32 v23, v24, v38
	v_mul_f32_e32 v23, v23, v28
	v_mul_f32_e32 v24, v25, v38
	v_mul_f32_e32 v24, v24, v29
	v_cvt_pk_bf16_f32 v23, v23, v24
	global_store_dwordx2 v[34:35], v[22:23], off offset:1024
	v_mov_b64_e32 v[22:23], v[224:225]
	v_mov_b64_e32 v[24:25], v[226:227]
	v_mul_f32_e32 v0, v18, v38
	v_mul_f32_e32 v18, v19, v38
	v_mul_f32_e32 v19, v21, v38
	v_mul_f32_e32 v0, v0, v22
	v_mul_f32_e32 v18, v18, v23
	v_cvt_pk_bf16_f32 v18, v0, v18
	v_mul_f32_e32 v0, v20, v38
	v_mul_f32_e32 v19, v19, v25
	v_add_co_u32_e32 v22, vcc, s90, v36
	v_mul_f32_e32 v0, v0, v24
	v_cvt_pk_bf16_f32 v19, v0, v19
	global_store_dwordx2 v[34:35], v[18:19], off offset:1536
	v_addc_co_u32_e32 v23, vcc, 0, v37, vcc
	v_mov_b64_e32 v[18:19], v[228:229]
	v_mov_b64_e32 v[20:21], v[230:231]
	v_mul_f32_e32 v0, v14, v38
	v_mul_f32_e32 v14, v15, v38
	v_mul_f32_e32 v15, v17, v38
	v_mul_f32_e32 v0, v0, v18
	v_mul_f32_e32 v14, v14, v19
	v_cvt_pk_bf16_f32 v14, v0, v14
	v_mul_f32_e32 v0, v16, v38
	v_mul_f32_e32 v15, v15, v21
	v_mul_f32_e32 v0, v0, v20
	v_cvt_pk_bf16_f32 v15, v0, v15
	global_store_dwordx2 v[34:35], v[14:15], off offset:2048
	v_mov_b64_e32 v[14:15], v[232:233]
	v_mov_b64_e32 v[16:17], v[234:235]
	v_mul_f32_e32 v0, v10, v38
	v_mul_f32_e32 v10, v11, v38
	v_mul_f32_e32 v11, v13, v38
	v_mul_f32_e32 v0, v0, v14
	v_mul_f32_e32 v10, v10, v15
	v_cvt_pk_bf16_f32 v10, v0, v10
	v_mul_f32_e32 v0, v12, v38
	v_mul_f32_e32 v11, v11, v17
	v_mul_f32_e32 v0, v0, v16
	v_cvt_pk_bf16_f32 v11, v0, v11
	global_store_dwordx2 v[34:35], v[10:11], off offset:2560
	v_mov_b64_e32 v[10:11], v[236:237]
	v_mov_b64_e32 v[12:13], v[238:239]
	v_mul_f32_e32 v0, v6, v38
	v_mul_f32_e32 v6, v7, v38
	v_mul_f32_e32 v7, v9, v38
	v_mul_f32_e32 v0, v0, v10
	v_mul_f32_e32 v6, v6, v11
	v_cvt_pk_bf16_f32 v6, v0, v6
	v_mul_f32_e32 v0, v8, v38
	v_mul_f32_e32 v7, v7, v13
	v_mul_f32_e32 v0, v0, v12
	v_cvt_pk_bf16_f32 v7, v0, v7
	global_store_dwordx2 v[34:35], v[6:7], off offset:3072
	v_mov_b64_e32 v[6:7], v[240:241]
	v_mov_b64_e32 v[8:9], v[242:243]
	v_mul_f32_e32 v0, v2, v38
	v_mul_f32_e32 v2, v3, v38
	v_mul_f32_e32 v3, v5, v38
	v_mul_f32_e32 v0, v0, v6
	v_mul_f32_e32 v2, v2, v7
	v_cvt_pk_bf16_f32 v2, v0, v2
	v_mul_f32_e32 v0, v4, v38
	v_mul_f32_e32 v3, v3, v9
	v_mul_f32_e32 v0, v0, v8
	v_cvt_pk_bf16_f32 v3, v0, v3
	global_store_dwordx2 v[34:35], v[2:3], off offset:3584
